# DSA scoring loop: the last iteration no longer prefetches key tiles nobody consumes (16 KB per wave per item; the top-k phase waited for them)
# speedup vs baseline: 1.0025x; 1.0025x over previous
;     ...
;       auto ldb = [&](bf16x8 (&kk)[4][4], int i0) {
; #pragma unroll
;           for (int j = 0; j < 4; ++j) { int T = wid + 8 * (i0 + j); T = T < ntile32 ? T : ntile32 - 1; const u16* kp = p.kiP + (((size_t)bl * 128 + T) * 256 + lane) * 8;
; #pragma unroll
;               for (int ks = 0; ks < 4; ++ks) kk[j][ks] = *(const bf16x8*)(kp + ks * 512); } };
;     ...
;           for (int i0 = 0; i0 < nT; i0 += 8) { ldb(kc, i0 + 4); comp(ka, i0); ldb(ka, i0 + 8); comp(kc, i0 + 4); }
.LBB0_187:
	s_add_i32 s27, s21, 8
	s_cmp_ge_i32 s27, s1
	s_cbranch_scc1 .Lb1_last
	s_sub_i32 s27, s22, 24
	s_min_i32 s28, s27, s20
	s_ashr_i32 s29, s28, 31
	s_lshl_b64 s[28:29], s[28:29], 12
	s_add_i32 s27, s22, -16
	v_lshl_add_u64 v[2:3], v[172:173], 0, s[28:29]
	s_min_i32 s28, s27, s20
	s_ashr_i32 s29, s28, 31
	s_lshl_b64 s[28:29], s[28:29], 12
	s_add_i32 s27, s22, -8
	global_load_dwordx4 v[126:129], v[2:3], off
	global_load_dwordx4 v[122:125], v[2:3], off offset:1024
	global_load_dwordx4 v[118:121], v[2:3], off offset:2048
	global_load_dwordx4 v[114:117], v[2:3], off offset:3072
	v_lshl_add_u64 v[2:3], v[172:173], 0, s[28:29]
	s_min_i32 s28, s27, s20
	s_ashr_i32 s29, s28, 31
	s_lshl_b64 s[28:29], s[28:29], 12
	global_load_dwordx4 v[94:97], v[2:3], off
	global_load_dwordx4 v[90:93], v[2:3], off offset:1024
	global_load_dwordx4 v[86:89], v[2:3], off offset:2048
	global_load_dwordx4 v[82:85], v[2:3], off offset:3072
	v_lshl_add_u64 v[2:3], v[172:173], 0, s[28:29]
	s_min_i32 s28, s22, s20
	s_ashr_i32 s29, s28, 31
	s_lshl_b64 s[28:29], s[28:29], 12
	global_load_dwordx4 v[62:65], v[2:3], off
	global_load_dwordx4 v[58:61], v[2:3], off offset:1024
	global_load_dwordx4 v[54:57], v[2:3], off offset:2048
	global_load_dwordx4 v[50:53], v[2:3], off offset:3072
	v_lshl_add_u64 v[2:3], v[172:173], 0, s[28:29]
	global_load_dwordx4 v[46:49], v[2:3], off
	global_load_dwordx4 v[42:45], v[2:3], off offset:1024
	global_load_dwordx4 v[38:41], v[2:3], off offset:2048
	global_load_dwordx4 v[34:37], v[2:3], off offset:3072
	s_cmp_ge_i32 s26, s0
	s_cbranch_scc0 .LBB0_194
	s_cmp_ge_i32 s25, s0
	s_cbranch_scc0 .LBB0_195

;     ...
;           for (int j = 0; j < 4; ++j) {
;               const int T = wid + 8 * (i0 + j);
;               if (T < ntile32) {
;     ...
;           for (int i0 = 0; i0 < nT; i0 += 8) { ldb(kc, i0 + 4); comp(ka, i0); ldb(ka, i0 + 8); comp(kc, i0 + 4); }
.Lb1_last:
	s_cmp_ge_i32 s26, s0
	s_cbranch_scc0 .Lb1l_194
	s_cmp_ge_i32 s25, s0
	s_cbranch_scc0 .Lb1l_195

;     ...
;           for (int j = 0; j < 4; ++j) {
;               const int T = wid + 8 * (i0 + j);
;               if (T < ntile32) {
;                   const int key = T * 32 + c32;
;                   f32x16 a;
; #pragma unroll
;                   for (int r = 0; r < 16; ++r) a[r] = 0.f;
; #pragma unroll
;                   for (int ks = 0; ks < 4; ++ks) a = __builtin_amdgcn_mfma_f32_32x32x16_bf16(qa[ks], kk[j][ks], a, 0, 0, 0);
; #pragma unroll
;                   for (int g4 = 0; g4 < 4; ++g4) { float s = 0.f;
; #pragma unroll
;                       for (int hh = 0; hh < 4; ++hh) s = fmaf(wv[4 * g4 + hh], fmaxf(a[4 * g4 + hh], 0.f), s);
;                       sc[(2 * g4 + hi) * 4096 + key] = s; }
;               }
.Lb1l_194:
	s_waitcnt vmcnt(15)
	v_mfma_f32_32x32x16_bf16 v[2:17], v[30:33], v[158:161], 0
	s_waitcnt vmcnt(14)
	v_mfma_f32_32x32x16_bf16 v[2:17], v[22:25], v[154:157], v[2:17]
	s_waitcnt vmcnt(13)
	v_mfma_f32_32x32x16_bf16 v[2:17], v[18:21], v[150:153], v[2:17]
	s_waitcnt vmcnt(12)
	v_mfma_f32_32x32x16_bf16 v[2:17], v[26:29], v[146:149], v[2:17]
	s_nop 11
	v_max_f32_e32 v2, v2, v2
	v_max_f32_e32 v6, v6, v6
	v_max_f32_e32 v3, v3, v3
	v_max_f32_e32 v7, v7, v7
	v_max_f32_e32 v2, 0, v2
	v_max_f32_e32 v6, 0, v6
	v_max_f32_e32 v4, v4, v4
	v_max_f32_e32 v8, v8, v8
	v_max_f32_e32 v10, v10, v10
	v_max_f32_e32 v3, 0, v3
	v_max_f32_e32 v7, 0, v7
	v_fma_f32 v2, v175, v2, 0
	v_fma_f32 v6, v179, v6, 0
	v_max_f32_e32 v5, v5, v5
	v_max_f32_e32 v9, v9, v9
	v_max_f32_e32 v11, v11, v11
	v_max_f32_e32 v4, 0, v4
	v_max_f32_e32 v8, 0, v8
	v_max_f32_e32 v10, 0, v10
	v_fmac_f32_e32 v2, v176, v3
	v_fmac_f32_e32 v6, v181, v7
	v_max_f32_e32 v12, v12, v12
	v_max_f32_e32 v5, 0, v5
	v_max_f32_e32 v9, 0, v9
	v_max_f32_e32 v11, 0, v11
	v_fma_f32 v10, v184, v10, 0
	v_fmac_f32_e32 v2, v177, v4
	v_fmac_f32_e32 v6, v182, v8
	v_max_f32_e32 v13, v13, v13
	v_max_f32_e32 v12, 0, v12
	v_fmac_f32_e32 v10, v185, v11
	v_fmac_f32_e32 v2, v178, v5
	v_fmac_f32_e32 v6, v183, v9
	v_fmac_f32_e32 v10, v186, v12
	ds_write2st64_b32 v0, v2, v6 offset0:16 offset1:144
	v_max_f32_e32 v2, 0, v13
	v_fmac_f32_e32 v10, v187, v2
	v_add_u32_e32 v2, 0x11000, v0
	ds_write_b32 v2, v10
	v_max_f32_e32 v2, v14, v14
	v_max_f32_e32 v2, 0, v2
	v_max_f32_e32 v3, v15, v15
	v_fma_f32 v2, v188, v2, 0
	v_max_f32_e32 v3, 0, v3
	v_fmac_f32_e32 v2, v189, v3
	v_max_f32_e32 v3, v16, v16
	v_max_f32_e32 v3, 0, v3
	v_fmac_f32_e32 v2, v190, v3
	v_max_f32_e32 v3, v17, v17
	v_max_f32_e32 v3, 0, v3
	v_fmac_f32_e32 v2, v191, v3
	v_add_u32_e32 v3, 0x19000, v0
	ds_write_b32 v3, v2
	s_cmp_ge_i32 s25, s0
	s_cbranch_scc1 .Lb1l_189
.Lb1l_195:
	s_waitcnt vmcnt(11)
	v_mfma_f32_32x32x16_bf16 v[2:17], v[30:33], v[142:145], 0
	s_waitcnt vmcnt(10)
	v_mfma_f32_32x32x16_bf16 v[2:17], v[22:25], v[138:141], v[2:17]
	s_waitcnt vmcnt(9)
	v_mfma_f32_32x32x16_bf16 v[2:17], v[18:21], v[134:137], v[2:17]
	s_waitcnt vmcnt(8)
	v_mfma_f32_32x32x16_bf16 v[2:17], v[26:29], v[130:133], v[2:17]
	s_nop 11
	v_max_f32_e32 v2, v2, v2
	v_max_f32_e32 v6, v6, v6
	v_max_f32_e32 v3, v3, v3
	v_max_f32_e32 v7, v7, v7
	v_max_f32_e32 v2, 0, v2
	v_max_f32_e32 v6, 0, v6
	v_max_f32_e32 v4, v4, v4
	v_max_f32_e32 v8, v8, v8
	v_max_f32_e32 v10, v10, v10
	v_max_f32_e32 v3, 0, v3
	v_max_f32_e32 v7, 0, v7
	v_fma_f32 v2, v175, v2, 0
	v_fma_f32 v6, v179, v6, 0
	v_max_f32_e32 v5, v5, v5
	v_max_f32_e32 v9, v9, v9
	v_max_f32_e32 v11, v11, v11
	v_max_f32_e32 v4, 0, v4
	v_max_f32_e32 v8, 0, v8
	v_max_f32_e32 v10, 0, v10
	v_fmac_f32_e32 v2, v176, v3
	v_fmac_f32_e32 v6, v181, v7
	v_max_f32_e32 v12, v12, v12
	v_max_f32_e32 v5, 0, v5
	v_max_f32_e32 v9, 0, v9
	v_max_f32_e32 v11, 0, v11
	v_fma_f32 v10, v184, v10, 0
	v_fmac_f32_e32 v2, v177, v4
	v_fmac_f32_e32 v6, v182, v8
	v_max_f32_e32 v13, v13, v13
	v_max_f32_e32 v12, 0, v12
	v_fmac_f32_e32 v10, v185, v11
	v_fmac_f32_e32 v2, v178, v5
	v_fmac_f32_e32 v6, v183, v9
	v_fmac_f32_e32 v10, v186, v12
	ds_write2st64_b32 v0, v2, v6 offset0:20 offset1:148
	v_max_f32_e32 v2, 0, v13
	v_fmac_f32_e32 v10, v187, v2
	v_add_u32_e32 v2, 0x11400, v0
	ds_write_b32 v2, v10
	v_max_f32_e32 v2, v14, v14
	v_max_f32_e32 v2, 0, v2
	v_max_f32_e32 v3, v15, v15
	v_fma_f32 v2, v188, v2, 0
	v_max_f32_e32 v3, 0, v3
	v_fmac_f32_e32 v2, v189, v3
	v_max_f32_e32 v3, v16, v16
	v_max_f32_e32 v3, 0, v3
	v_fmac_f32_e32 v2, v190, v3
	v_max_f32_e32 v3, v17, v17
	v_max_f32_e32 v3, 0, v3
	v_fmac_f32_e32 v2, v191, v3
	v_add_u32_e32 v3, 0x19400, v0
	ds_write_b32 v3, v2
	s_cmp_ge_i32 s24, s0
	s_cbranch_scc1 .Lb1l_190
;     ...
;           for (int j = 0; j < 4; ++j) {
;               const int T = wid + 8 * (i0 + j);
;               if (T < ntile32) {
;                   const int key = T * 32 + c32;
;                   f32x16 a;
; #pragma unroll
;                   for (int r = 0; r < 16; ++r) a[r] = 0.f;
; #pragma unroll
;                   for (int ks = 0; ks < 4; ++ks) a = __builtin_amdgcn_mfma_f32_32x32x16_bf16(qa[ks], kk[j][ks], a, 0, 0, 0);
; #pragma unroll
;                   for (int g4 = 0; g4 < 4; ++g4) { float s = 0.f;
; #pragma unroll
;                       for (int hh = 0; hh < 4; ++hh) s = fmaf(wv[4 * g4 + hh], fmaxf(a[4 * g4 + hh], 0.f), s);
;                       sc[(2 * g4 + hi) * 4096 + key] = s; }
;               }
.Lb1l_196:
	s_waitcnt vmcnt(7)
	v_mfma_f32_32x32x16_bf16 v[2:17], v[30:33], v[110:113], 0
	s_waitcnt vmcnt(6)
	v_mfma_f32_32x32x16_bf16 v[2:17], v[22:25], v[106:109], v[2:17]
	s_waitcnt vmcnt(5)
	v_mfma_f32_32x32x16_bf16 v[2:17], v[18:21], v[102:105], v[2:17]
	s_waitcnt vmcnt(4)
	v_mfma_f32_32x32x16_bf16 v[2:17], v[26:29], v[98:101], v[2:17]
	s_nop 11
	v_max_f32_e32 v2, v2, v2
	v_max_f32_e32 v6, v6, v6
	v_max_f32_e32 v3, v3, v3
	v_max_f32_e32 v7, v7, v7
	v_max_f32_e32 v2, 0, v2
	v_max_f32_e32 v6, 0, v6
	v_max_f32_e32 v4, v4, v4
	v_max_f32_e32 v8, v8, v8
	v_max_f32_e32 v10, v10, v10
	v_max_f32_e32 v3, 0, v3
	v_max_f32_e32 v7, 0, v7
	v_fma_f32 v2, v175, v2, 0
	v_fma_f32 v6, v179, v6, 0
	v_max_f32_e32 v5, v5, v5
	v_max_f32_e32 v9, v9, v9
	v_max_f32_e32 v11, v11, v11
	v_max_f32_e32 v4, 0, v4
	v_max_f32_e32 v8, 0, v8
	v_max_f32_e32 v10, 0, v10
	v_fmac_f32_e32 v2, v176, v3
	v_fmac_f32_e32 v6, v181, v7
	v_max_f32_e32 v12, v12, v12
	v_max_f32_e32 v5, 0, v5
	v_max_f32_e32 v9, 0, v9
	v_max_f32_e32 v11, 0, v11
	v_fma_f32 v10, v184, v10, 0
	v_fmac_f32_e32 v2, v177, v4
	v_fmac_f32_e32 v6, v182, v8
	v_max_f32_e32 v13, v13, v13
	v_max_f32_e32 v12, 0, v12
	v_fmac_f32_e32 v10, v185, v11
	v_fmac_f32_e32 v2, v178, v5
	v_fmac_f32_e32 v6, v183, v9
	v_fmac_f32_e32 v10, v186, v12
	ds_write2st64_b32 v0, v2, v6 offset0:24 offset1:152
	v_max_f32_e32 v2, 0, v13
	v_fmac_f32_e32 v10, v187, v2
	v_add_u32_e32 v2, 0x11800, v0
	ds_write_b32 v2, v10
	v_max_f32_e32 v2, v14, v14
	v_max_f32_e32 v2, 0, v2
	v_max_f32_e32 v3, v15, v15
	v_fma_f32 v2, v188, v2, 0
	v_max_f32_e32 v3, 0, v3
	v_fmac_f32_e32 v2, v189, v3
	v_max_f32_e32 v3, v16, v16
	v_max_f32_e32 v3, 0, v3
	v_fmac_f32_e32 v2, v190, v3
	v_max_f32_e32 v3, v17, v17
	v_max_f32_e32 v3, 0, v3
	v_fmac_f32_e32 v2, v191, v3
	v_add_u32_e32 v3, 0x19800, v0
	ds_write_b32 v3, v2
	s_cmp_ge_i32 s23, s0
	s_cbranch_scc1 .LBB0_181
.Lb1l_197:
	s_waitcnt vmcnt(3)
	v_mfma_f32_32x32x16_bf16 v[2:17], v[30:33], v[78:81], 0
	s_waitcnt vmcnt(2)
	v_mfma_f32_32x32x16_bf16 v[2:17], v[22:25], v[74:77], v[2:17]
	s_waitcnt vmcnt(1)
	v_mfma_f32_32x32x16_bf16 v[2:17], v[18:21], v[70:73], v[2:17]
	s_waitcnt vmcnt(0)
	v_mfma_f32_32x32x16_bf16 v[2:17], v[26:29], v[66:69], v[2:17]
	s_nop 11
	v_max_f32_e32 v2, v2, v2
	v_max_f32_e32 v6, v6, v6
	v_max_f32_e32 v3, v3, v3
	v_max_f32_e32 v7, v7, v7
	v_max_f32_e32 v2, 0, v2
	v_max_f32_e32 v6, 0, v6
	v_max_f32_e32 v4, v4, v4
	v_max_f32_e32 v8, v8, v8
	v_max_f32_e32 v10, v10, v10
	v_max_f32_e32 v3, 0, v3
	v_max_f32_e32 v7, 0, v7
	v_fma_f32 v2, v175, v2, 0
	v_fma_f32 v6, v179, v6, 0
	v_max_f32_e32 v5, v5, v5
	v_max_f32_e32 v9, v9, v9
	v_max_f32_e32 v11, v11, v11
	v_max_f32_e32 v4, 0, v4
	v_max_f32_e32 v8, 0, v8
	v_max_f32_e32 v10, 0, v10
	v_fmac_f32_e32 v2, v176, v3
	v_fmac_f32_e32 v6, v181, v7
	v_max_f32_e32 v12, v12, v12
	v_max_f32_e32 v5, 0, v5
	v_max_f32_e32 v9, 0, v9
	v_max_f32_e32 v11, 0, v11
	v_fma_f32 v10, v184, v10, 0
	v_fmac_f32_e32 v2, v177, v4
	v_fmac_f32_e32 v6, v182, v8
	v_max_f32_e32 v13, v13, v13
	v_max_f32_e32 v12, 0, v12
	v_fmac_f32_e32 v10, v185, v11
	v_fmac_f32_e32 v2, v178, v5
	v_fmac_f32_e32 v6, v183, v9
	v_fmac_f32_e32 v10, v186, v12
	ds_write2st64_b32 v0, v2, v6 offset0:28 offset1:156
	v_max_f32_e32 v2, 0, v13
	v_fmac_f32_e32 v10, v187, v2
	v_add_u32_e32 v2, 0x11c00, v0
	ds_write_b32 v2, v10
	v_max_f32_e32 v2, v14, v14
	v_max_f32_e32 v2, 0, v2
	v_max_f32_e32 v3, v15, v15
	v_fma_f32 v2, v188, v2, 0
	v_max_f32_e32 v3, 0, v3
	v_fmac_f32_e32 v2, v189, v3
	v_max_f32_e32 v3, v16, v16
	v_max_f32_e32 v3, 0, v3
	v_fmac_f32_e32 v2, v190, v3
	v_max_f32_e32 v3, v17, v17
	v_max_f32_e32 v3, 0, v3
	v_fmac_f32_e32 v2, v191, v3
	v_add_u32_e32 v3, 0x19c00, v0
	ds_write_b32 v3, v2
	s_branch .LBB0_181
